# RG-LRU fifth round (64 ctx tiles) spread over the first halves of blocks 0..63 (one active wave per SIMD), Fourier extras rotated to blocks 64..95
# speedup vs baseline: 1.0017x; 1.0017x over previous
; __device__ __forceinline__ void lru_tile(const Params& P, int chunk, int head, int pass, char* smem_raw) {
;   u16* sm_uc = reinterpret_cast<u16*>(smem_raw);
;   u16* sm_w = sm_uc + 128 * LDSS;
;   float* sm_a = reinterpret_cast<float*>(sm_w + 128 * LDSS);
;   float* sm_b = sm_a + 64 * 64;
;   float2* sm_ph = reinterpret_cast<float2*>(sm_b + 64 * 64);
;   float* sm_init = reinterpret_cast<float*>(sm_ph + 256);
;   const int tid = VTID, lane = tid & 63, wid = tid >> 6;
;   const int q = tid >> 6, ch = tid & 63;
;   const int row0 = chunk * 128;
;   int seq_lo, seq_hi;
;   if (chunk < 256) { seq_lo = (chunk >> 6) << 13; seq_hi = seq_lo + 8192; }
;   else { const int b = (chunk - 256) >> 1; seq_lo = N_X + b * 256; seq_hi = seq_lo + 256; }
;   const int gch = head * 64 + ch;
;   const float* hfbuf = reinterpret_cast<const float*>(P.hy);
;   float* hfw = reinterpret_cast<float*>(P.hy);
; __device__ __forceinline__ void run_phase(const Params& P, const int ph, char* smem_raw) {
;     ...
;     case 3:
;       for (int t = VBID; t < 2112; t += VGRID) lru_tile(P, t >> 3, t & 7, 1, smv_raw);
;       for (int t = VBID; t < 2112; t += VGRID) fourier_stepA_tile(P, t, smv);
.LBB0_287:
	v_readlane_b32 s0, v252, 0
	v_readlane_b32 s1, v252, 1
	v_readfirstlane_b32 s68, v153
	s_nop 3
	s_sub_u32 s0, s0, 0x170
	s_subb_u32 s1, s1, 0
	s_load_dwordx2 s[10:11], s[0:1], 0x148
	s_load_dwordx2 s[12:13], s[0:1], 0x158
	s_load_dwordx2 s[18:19], s[0:1], 0x130
	s_load_dwordx2 s[20:21], s[0:1], 0x128
	s_load_dwordx4 s[24:27], s[0:1], 0x70
	s_load_dwordx2 s[28:29], s[0:1], 0x88
	s_load_dwordx2 s[30:31], s[0:1], 0x98
	s_load_dwordx2 s[36:37], s[0:1], 0xa0
	s_lshl_b32 s4, s2, 1
	s_add_u32 s68, s4, s68
	s_mov_b32 s69, 0
	s_mov_b32 s70, 4
	s_cmp_lt_u32 s68, 128
	s_cselect_b32 s70, 5, 4
	s_mov_b32 s72, 0xffff0000
	s_mov_b32 s73, -1
	s_mov_b32 s74, 0
	s_mov_b32 s75, -1
	s_mov_b32 s76, 0
	s_mov_b32 s77, 0xffff0000
	s_mov_b32 s78, -1
	s_mov_b32 s79, 0x0000ffff
	s_mov_b32 s80, -1
	s_mov_b32 s81, 0
	s_mov_b32 s82, 0x0000ffff
	s_mov_b32 s83, 0
	v_and_b32_e32 v138, 63, v152
	v_lshrrev_b32_e32 v139, 4, v138
	v_and_b32_e32 v140, 15, v138
	v_bfe_u32 v141, v152, 6, 2
	v_lshl_add_u32 v255, v141, 4, v140
	v_mul_u32_u24_e32 v253, 0x12000, v153
	v_add_u32_e32 v253, 16, v253
	v_mul_u32_u24_e32 v134, 0x18000, v139
	v_lshl_add_u32 v134, v255, 1, v134
	v_lshlrev_b32_e32 v237, 16, v139
	v_lshl_add_u32 v237, v255, 1, v237
	v_lshlrev_b32_e32 v250, 3, v255
	v_lshlrev_b32_e32 v251, 7, v255
	v_lshl_add_u32 v251, v139, 4, v251
	v_lshrrev_b32_e32 v254, 3, v140
	v_lshl_add_u32 v254, v141, 1, v254
	v_lshlrev_b32_e32 v202, 1, v139
	v_xor_b32_e32 v89, v254, v202
	v_xor_b32_e32 v130, 1, v89
	v_and_b32_e32 v203, 7, v140
	v_lshl_add_u32 v202, v139, 12, v253
	v_lshl_add_u32 v202, v203, 1, v202
	v_lshl_add_u32 v89, v89, 4, v202
	v_lshl_add_u32 v130, v130, 4, v202
	v_lshrrev_b32_e32 v202, 2, v140
	v_and_b32_e32 v203, 3, v140
	v_lshl_add_u32 v254, v202, 5, v203
	v_lshl_add_u32 v254, v254, 7, v253
	v_lshrrev_b32_e32 v203, 1, v203
	v_lshl_add_u32 v202, v202, 1, v203
	v_xor_b32_e32 v202, v139, v202
	v_lshl_add_u32 v131, v202, 4, v254
	v_xor_b32_e32 v202, 4, v202
	v_lshl_add_u32 v133, v202, 4, v254
	v_cmp_eq_u32_e32 vcc, 0, v139
	s_mov_b64 s[84:85], vcc
	v_cmp_eq_u32_e32 vcc, 3, v139
	s_mov_b64 s[86:87], vcc
	s_waitcnt lgkmcnt(0)
.Lmy_lrua_tile:
	s_lshl_b32 s4, s69, 9
	s_add_u32 s4, s4, s68
	s_cmp_eq_u32 s69, 4
	s_cbranch_scc0 .Lmy_lrua_t5n
	s_and_b32 s5, s68, 1
	s_cmp_eq_u32 s5, 1
	s_cbranch_scc0 .Lmy_lrua_t5e
	s_barrier
	s_barrier
	s_branch .Lmy_lrua_next
.Lmy_lrua_t5e:
	s_lshr_b32 s4, s68, 1
	s_add_u32 s4, s4, 0x800
.Lmy_lrua_t5n:
	s_lshr_b32 s71, s4, 3
	s_and_b32 s5, s4, 7
	s_lshl_b32 s56, s5, 6
	s_cmp_lt_u32 s71, 256
	s_cbranch_scc0 .Lmy_lrua_ctx
	s_and_b32 s57, s71, 63
	s_mov_b32 s60, 63
	s_branch .Lmy_lrua_fl

; __device__ __forceinline__ void run_phase(const Params& P, const int ph, char* smem_raw) {
;     ...
;       for (int t = VBID; t < 2112; t += VGRID) lru_tile(P, t >> 3, t & 7, 1, smv_raw);
;       for (int t = VBID; t < 2112; t += VGRID) fourier_stepA_tile(P, t, smv);
.Lmy_lrua_next:
	s_add_u32 s69, s69, 1
	s_cmp_lt_u32 s69, s70
	s_cbranch_scc1 .Lmy_lrua_tile
	s_waitcnt lgkmcnt(0)
	s_barrier
.LBB0_417:
	s_or_b64 exec, exec, s[8:9]
	v_add_u32_e32 v86, 0x180, v86
	v_and_b32_e32 v86, 0x1ff, v86
	v_mul_u32_u24_e32 v1, 0x600, v72
	s_movk_i32 s0, 0x48
	v_or_b32_e32 v8, v1, v48
	v_mad_u32_u24 v1, v69, s0, v48
	v_and_b32_e32 v3, 8, v66
	v_lshl_add_u32 v89, v1, 1, v49
	v_and_b32_e32 v1, 31, v152
	v_lshlrev_b32_e32 v3, 1, v3
	v_and_or_b32 v1, v64, 64, v1
	v_add_u32_e32 v5, v49, v3
	s_movk_i32 s0, 0x90
	v_mov_b32_e32 v65, 0
	v_lshlrev_b32_e32 v4, 7, v69
	v_mad_u32_u24 v90, v1, s0, v5
	v_and_b32_e32 v1, 0x5f, v152
	v_lshlrev_b32_e32 v64, 1, v48
	v_mul_u32_u24_e32 v0, 0x600, v69
	v_mul_u32_u24_e32 v1, 0x48, v1
	v_lshl_add_u64 v[10:11], s[42:43], 0, v[64:65]
	v_or_b32_e32 v64, 0x1000, v4
	v_or_b32_e32 v0, v0, v48
	v_lshlrev_b32_e32 v1, 1, v1
	v_lshl_add_u64 v[68:69], v[10:11], 0, v[64:65]
	v_or_b32_e32 v64, 0x2000, v4
	v_add_u32_e32 v2, 0xc000, v0
	v_add_u32_e32 v6, 0x18000, v0
	v_add3_u32 v91, v49, v1, v3
	v_add_u32_e32 v92, v5, v1
	v_mov_b32_e32 v5, v65
	v_lshl_add_u64 v[70:71], v[10:11], 0, v[64:65]
	v_lshlrev_b32_e32 v64, 7, v72
	s_add_u32 s0, s90, 0x6300000
	v_lshlrev_b32_e32 v1, 6, v153
	v_lshl_add_u64 v[66:67], v[10:11], 0, v[4:5]
	v_lshl_add_u64 v[72:73], v[10:11], 0, v[64:65]
	s_addc_u32 s1, s91, 0
	v_lshl_add_u32 v93, s2, 7, v1
	s_lshl_b32 s8, s96, 7
	s_mov_b64 s[4:5], 0
	s_mov_b32 s9, 0x60000
	v_mov_b64_e32 v[74:75], s[90:91]
	v_lshlrev_b32_e32 v76, 1, v0
	v_mov_b32_e32 v77, v65
	v_lshlrev_b32_e32 v78, 1, v2
	v_mov_b32_e32 v79, v65
	v_lshlrev_b32_e32 v80, 1, v6
	v_mov_b32_e32 v81, v65
	v_lshlrev_b32_e32 v82, 1, v8
	v_mov_b32_e32 v83, v65
	s_movk_i32 s10, 0x200
	s_mov_b32 s11, 0x3fffc0
	s_movk_i32 s12, 0x83f

; __device__ __forceinline__ void nn_phase(const Params& P, int set, u16* smem) {
;   const int nT = (set == 0) ? 2080 : 1024;
;   for (int t = VBID; t < nT; t += VGRID) {
;     const u16 *Ab, *Bb; u16* Cb; unsigned lda, s1, s2, e1, e2; int K;
;     const u16* G = P.zq + (long)N_TOK * 1536;
;     const int nt = t & 3;
;     if (set == 0 && t < 2048) {
; __device__ __forceinline__ void run_phase(const Params& P, const int ph, char* smem_raw) {
;     ...
;     case 4:
;       for (int t = VBID; t < 2112; t += VGRID) lru_tile(P, t >> 3, t & 7, 2, smv_raw);
;       nn_phase(P, 0, smv);
.Lmy_lrub_next:
	s_add_u32 s69, s69, 1
	s_cmp_lt_u32 s69, s70
	s_cbranch_scc1 .Lmy_lrub_tile
	s_waitcnt lgkmcnt(0)
	s_barrier
	s_branch .LBB0_680
.LBB0_680:
	s_or_b64 exec, exec, s[16:17]
	v_add_u32_e32 v74, 0x180, v74
	v_and_b32_e32 v74, 0x1ff, v74
	s_movk_i32 s0, 0x820
	v_cmp_gt_i32_e32 vcc, s0, v74
	s_and_saveexec_b64 s[0:1], vcc
	s_cbranch_execz .LBB0_689
	v_lshrrev_b32_e32 v0, 3, v152
	v_lshlrev_b32_e32 v1, 3, v152
	v_or_b32_e32 v79, 0x60, v0
	v_lshrrev_b32_e32 v0, 1, v152
	v_and_b32_e32 v2, 31, v152
	v_and_b32_e32 v76, 56, v1
	v_lshrrev_b32_e32 v1, 4, v152
	v_and_or_b32 v0, v0, 64, v2
	v_lshrrev_b32_e32 v2, 2, v152
	v_bfe_u32 v75, v152, 3, 5
	v_and_b32_e32 v77, 0x7f, v152
	v_and_b32_e32 v1, 8, v1
	s_movk_i32 s3, 0x48
	v_and_b32_e32 v2, 8, v2
	v_mad_u32_u24 v80, v77, s3, v1
	v_mad_u32_u24 v81, v75, s3, v76
	v_mad_u32_u24 v84, v79, s3, v76
	v_and_b32_e32 v3, 0x5f, v152
	v_mad_u32_u24 v86, v0, s3, v2
	s_add_u32 s4, s90, 0x6300000
	s_movk_i32 s8, 0x8000
	v_lshrrev_b32_e32 v78, 1, v1
	v_lshl_add_u32 v82, v81, 1, v71
	v_lshl_add_u32 v83, v80, 1, v71
	v_lshl_add_u32 v85, v84, 1, v71
	v_mad_u32_u24 v87, v3, s3, v2
	v_and_b32_e32 v88, 0xff, v152
	s_addc_u32 s5, s91, 0
	s_lshl_b32 s3, s96, 1
	v_add_u32_e32 v89, 16, v86
	v_add_u32_e32 v90, 32, v86
	v_add_u32_e32 v91, 48, v86
	v_or_b32_e32 v92, 64, v1
	v_or_b32_e32 v93, 64, v76
	s_mov_b64 s[6:7], 0
	s_movk_i32 s14, 0x7ff
	v_mov_b32_e32 v65, 0
	s_mov_b32 s9, -1
	s_mov_b64 s[10:11], 0x400
	s_movk_i32 s15, 0x81f
